# grid barrier: each XCD's last arriver adds to every XCD's completion word after its write-back; all waiters poll their own XCD's word (no top-level counter round trip, no separate release)
# speedup vs baseline: 1.0019x; 1.0019x over previous
.LBB0_476:
	s_or_b64 exec, exec, s[30:31]
	s_waitcnt vmcnt(0)
	v_readfirstlane_b32 s25, v3
	v_sub_u32_e32 v4, 0, v2
	s_nop 0
	v_add_u32_e32 v3, s25, v1
	v_cvt_f32_u32_e32 v1, v2
	v_rcp_iflag_f32_e32 v1, v1
	s_nop 0
	v_mul_f32_e32 v1, 0x4f7ffffe, v1
	v_cvt_u32_f32_e32 v1, v1
	v_mul_lo_u32 v4, v4, v1
	v_mul_hi_u32 v4, v1, v4
	v_add_u32_e32 v1, v1, v4
	v_mul_hi_u32 v1, v3, v1
	v_mul_lo_u32 v4, v1, v2
	v_sub_u32_e32 v4, v3, v4
	v_cmp_ge_u32_e32 vcc, v4, v2
	v_add_u32_e32 v5, 1, v1
	s_nop 0
	v_cndmask_b32_e32 v1, v1, v5, vcc
	v_sub_u32_e32 v5, v4, v2
	v_cndmask_b32_e32 v4, v4, v5, vcc
	v_cmp_ge_u32_e32 vcc, v4, v2
	v_add_u32_e32 v4, 1, v1
	s_nop 0
	v_cndmask_b32_e32 v1, v1, v4, vcc
	v_add_u32_e32 v4, 1, v3
	v_add_u32_e32 v17, 1, v1
	v_mad_u64_u32 v[2:3], s[26:27], v2, v1, v[2:3]
	v_mul_lo_u32 v17, v17, v0
	v_cmp_ne_u32_e32 vcc, v4, v2
	s_and_saveexec_b64 s[26:27], vcc
	s_xor_b64 s[30:31], exec, s[26:27]
	s_cbranch_execz .LBB0_490
	v_readlane_b32 s26, v254, 39
	v_readlane_b32 s27, v254, 40
	s_nop 4
	global_load_dword v0, v129, s[26:27] sc1
	s_waitcnt vmcnt(0)
	v_cmp_lt_u32_e32 vcc, v0, v17
	s_and_saveexec_b64 s[36:37], vcc
	s_cbranch_execz .LBB0_489
	s_mov_b32 s25, 1
	s_mov_b64 s[38:39], 0
	s_branch .LBB0_480

.LBB0_482:
	v_readlane_b32 s26, v254, 39
	v_readlane_b32 s27, v254, 40
	s_add_i32 s25, s25, 1
	s_mov_b64 s[44:45], -1
	s_nop 2
	global_load_dword v0, v129, s[26:27] sc1
	s_waitcnt vmcnt(0)
	v_cmp_ge_u32_e32 vcc, v0, v17
	s_orn2_b64 s[42:43], vcc, exec
	s_branch .LBB0_479

.LBB0_490:
	s_andn2_saveexec_b64 s[26:27], s[30:31]
	s_cbranch_execz .LBB0_510
	s_mov_b64 s[30:31], exec
	buffer_wbl2 sc1
	s_waitcnt lgkmcnt(0)
	s_waitcnt vmcnt(0)
	v_readlane_b32 s26, v254, 43
	v_readlane_b32 s27, v254, 44
	v_mov_b32_e32 v4, 1
	s_sub_u32 s26, s26, 0x1100
	s_subb_u32 s27, s27, 0
	global_atomic_add v129, v4, s[26:27]
	global_atomic_add v129, v4, s[26:27] offset:256
	global_atomic_add v129, v4, s[26:27] offset:512
	global_atomic_add v129, v4, s[26:27] offset:768
	global_atomic_add v129, v4, s[26:27] offset:1024
	global_atomic_add v129, v4, s[26:27] offset:1280
	global_atomic_add v129, v4, s[26:27] offset:1536
	global_atomic_add v129, v4, s[26:27] offset:1792
	global_atomic_add v129, v4, s[26:27] offset:2048
	global_atomic_add v129, v4, s[26:27] offset:2304
	global_atomic_add v129, v4, s[26:27] offset:2560
	global_atomic_add v129, v4, s[26:27] offset:2816
	global_atomic_add v129, v4, s[26:27] offset:3072
	global_atomic_add v129, v4, s[26:27] offset:3328
	global_atomic_add v129, v4, s[26:27] offset:3584
	global_atomic_add v129, v4, s[26:27] offset:3840
	s_mov_b64 s[36:37], -1
	v_readlane_b32 s26, v254, 39
	v_readlane_b32 s27, v254, 40
	s_mov_b64 s[38:39], 0
	s_nop 3
	global_load_dword v0, v129, s[26:27] sc1
	s_waitcnt vmcnt(0)
	v_cmp_lt_u32_e32 vcc, v0, v17
	s_and_saveexec_b64 s[36:37], vcc
	s_cbranch_execz .LBB0_504
	s_mov_b32 s25, 1
	s_branch .LBB0_497

.LBB0_504:
	s_or_b64 exec, exec, s[36:37]
	v_readlane_b32 s26, v253, 49
	v_readlane_b32 s27, v253, 50
	s_orn2_b64 s[36:37], s[38:39], exec
	s_nop 0
	v_mov_b64_e32 v[0:1], s[26:27]
	s_branch .LBB0_505
.LBB0_505:
	s_or_b64 exec, exec, s[30:31]
	s_and_saveexec_b64 s[30:31], s[36:37]
	s_cbranch_execz .LBB0_507
	v_mov_b32_e32 v2, 1
	global_atomic_add v[0:1], v2, off
